# FoX unit prologue: the two dependent F2 gather round trips merged into one (third load issued with the first two, shared operand reused)
# speedup vs baseline: 1.0116x; 1.0052x over previous
; __device__ __forceinline__ void fox_unit(int b, int hh, int qb, const bf16_t* Q, const bf16_t* __restrict__ K, const bf16_t* __restrict__ V, bf16_t* O, ...
;     ...
;     for (int d0 = 0; d0 < 4; ++d0) { qr[d0] = *reinterpret_cast<const bf16x8*>(Qw + (long)r32 * DM + d0 * 16 + hi * 8);
; #pragma unroll
;         for (int j = 0; j < 8; ++j) { const float f = __builtin_bit_cast(float, (unsigned)(unsigned short)qr[d0][j] << 16); qn2 += f * f; } }
;     qn2 += other_half(qn2);
;     const float kn = sqrtf(2.0f * __uint_as_float(KMAX[b * 8 + hh])) * 1.01f;
;     const float zq = sqrtf(qn2) * kn * 1.01f + 1.0f;
;     const float ft2 = Frow[qw0 + r32];
;     const float f2q0 = Frow[q0];
;     int jp_last0;
;     { bool c = false; if (lane >= 1 && lane < NT / 2) c = (f2q0 - Frow[128 * lane - 1]) < -128.0f;
;       const unsigned long long mk = __ballot(c); jp_last0 = mk ? 63 - __builtin_clzll(mk) : 0; }
;     int jp_lastw;
;     { const float f2w0 = Frow[qw0]; bool c = false; if (lane >= 1 && lane < NT / 2) c = (f2w0 - Frow[128 * lane - 1]) < -128.0f;
;       const unsigned long long mk = __ballot(c); jp_lastw = mk ? 63 - __builtin_clzll(mk) : 0; }
.LBB0_413:
	s_lshl_b32 s7, s15, 5
	v_writelane_b32 v249, s16, 60
	s_add_i32 s70, s7, s10
	v_writelane_b32 v249, s15, 61
	s_add_i32 s80, s70, s12
	s_lshl_b32 s6, s16, 6
	s_lshl_b64 s[12:13], s[80:81], 11
	v_readlane_b32 s14, v249, 23
	v_readlane_b32 s15, v249, 24
	s_add_u32 s12, s14, s12
	s_addc_u32 s13, s15, s13
	s_lshl_b32 s6, s6, 1
	s_add_u32 s12, s12, s6
	s_addc_u32 s13, s13, 0
	v_lshlrev_b32_e32 v2, 1, v134
	v_lshl_add_u64 v[4:5], s[12:13], 0, v[2:3]
	v_lshlrev_b32_e32 v2, 1, v136
	v_lshl_add_u64 v[4:5], v[4:5], 0, v[2:3]
	global_load_dwordx4 v[118:121], v[4:5], off
	global_load_dwordx4 v[122:125], v[4:5], off offset:32
	global_load_dwordx4 v[126:129], v[4:5], off offset:64
	global_load_dwordx4 v[130:133], v[4:5], off offset:96
	v_writelane_b32 v249, s6, 62
	s_lshl_b32 s6, s11, 2
	v_readlane_b32 s12, v249, 21
	v_readlane_b32 s13, v249, 22
	s_add_u32 s12, s12, s6
	s_addc_u32 s13, s13, 0
	s_lshl_b32 s6, s2, 2
	s_lshl_b32 s2, s5, 2
	v_readlane_b32 s14, v249, 43
	v_or_b32_e32 v2, s70, v182
	v_mov_b32_e32 v6, s2
	v_readlane_b32 s15, v249, 44
	v_lshl_add_u64 v[4:5], v[2:3], 2, s[12:13]
	s_nop 3
	global_load_dword v6, v6, s[14:15] offset:256
	s_nop 0
	global_load_dword v2, v[4:5], off
	s_add_i32 s5, s6, 4
	s_lshr_b32 s2, s5, 1
	v_readlane_b32 s14, v249, 47
	v_cmp_gt_u32_e32 vcc, s2, v180
	v_readlane_b32 s15, v249, 48
	s_mov_b64 s[16:17], 0
	v_lshl_add_u64 v[4:5], v[150:151], 2, s[12:13]
	s_and_b64 s[14:15], s[14:15], vcc
	s_mov_b64 s[20:21], 0
	s_waitcnt vmcnt(5)
	v_and_b32_e32 v18, 0xffff0000, v118
	v_lshlrev_b32_e32 v7, 16, v118
	v_mul_f32_e32 v37, v18, v18
	v_lshlrev_b32_e32 v19, 16, v119
	v_fmac_f32_e32 v37, v7, v7
	v_and_b32_e32 v20, 0xffff0000, v119
	v_fmac_f32_e32 v37, v19, v19
	v_lshlrev_b32_e32 v21, 16, v120
	v_fmac_f32_e32 v37, v20, v20
	v_and_b32_e32 v22, 0xffff0000, v120
	v_fmac_f32_e32 v37, v21, v21
	v_lshlrev_b32_e32 v23, 16, v121
	v_fmac_f32_e32 v37, v22, v22
	v_and_b32_e32 v24, 0xffff0000, v121
	v_fmac_f32_e32 v37, v23, v23
	s_waitcnt vmcnt(4)
	v_lshlrev_b32_e32 v25, 16, v122
	v_fmac_f32_e32 v37, v24, v24
	v_and_b32_e32 v26, 0xffff0000, v122
	v_fmac_f32_e32 v37, v25, v25
	v_lshlrev_b32_e32 v27, 16, v123
	v_fmac_f32_e32 v37, v26, v26
	v_and_b32_e32 v28, 0xffff0000, v123
	v_fmac_f32_e32 v37, v27, v27
	v_lshlrev_b32_e32 v29, 16, v124
	v_fmac_f32_e32 v37, v28, v28
	v_and_b32_e32 v30, 0xffff0000, v124
	v_fmac_f32_e32 v37, v29, v29
	v_lshlrev_b32_e32 v31, 16, v125
	v_fmac_f32_e32 v37, v30, v30
	v_and_b32_e32 v32, 0xffff0000, v125
	v_fmac_f32_e32 v37, v31, v31
	s_waitcnt vmcnt(3)
	v_lshlrev_b32_e32 v33, 16, v126
	v_fmac_f32_e32 v37, v32, v32
	v_and_b32_e32 v34, 0xffff0000, v126
	v_fmac_f32_e32 v37, v33, v33
	v_lshlrev_b32_e32 v35, 16, v127
	v_fmac_f32_e32 v37, v34, v34
	v_and_b32_e32 v36, 0xffff0000, v127
	v_and_b32_e32 v9, 0xffff0000, v128
	v_lshlrev_b32_e32 v8, 16, v128
	v_fmac_f32_e32 v37, v35, v35
	v_pk_mul_f32 v[8:9], v[8:9], v[8:9]
	v_fmac_f32_e32 v37, v36, v36
	v_and_b32_e32 v11, 0xffff0000, v129
	v_lshlrev_b32_e32 v10, 16, v129
	v_add_f32_e32 v7, v8, v37
	v_pk_mul_f32 v[10:11], v[10:11], v[10:11]
	v_add_f32_e32 v7, v9, v7
	s_waitcnt vmcnt(2)
	v_and_b32_e32 v13, 0xffff0000, v130
	v_lshlrev_b32_e32 v12, 16, v130
	v_add_f32_e32 v7, v10, v7
	v_pk_mul_f32 v[12:13], v[12:13], v[12:13]
	v_add_f32_e32 v7, v11, v7
	v_and_b32_e32 v15, 0xffff0000, v131
	v_lshlrev_b32_e32 v14, 16, v131
	v_add_f32_e32 v7, v12, v7
	v_pk_mul_f32 v[14:15], v[14:15], v[14:15]
	v_add_f32_e32 v7, v13, v7
	v_and_b32_e32 v17, 0xffff0000, v132
	v_lshlrev_b32_e32 v16, 16, v132
	v_add_f32_e32 v7, v14, v7
	v_pk_mul_f32 v[16:17], v[16:17], v[16:17]
	v_add_f32_e32 v7, v15, v7
	v_and_b32_e32 v19, 0xffff0000, v133
	v_lshlrev_b32_e32 v18, 16, v133
	v_add_f32_e32 v7, v16, v7
	v_pk_mul_f32 v[18:19], v[18:19], v[18:19]
	v_add_f32_e32 v7, v17, v7
	v_add_f32_e32 v7, v18, v7
	v_add_f32_e32 v7, v19, v7
	v_mov_b32_e32 v8, v7
	v_mov_b32_e32 v9, v7
	s_nop 1
	v_permlane32_swap_b32_e32 v8, v9
	s_and_saveexec_b64 s[18:19], s[14:15]
	s_cbranch_execz .LBB0_415
	s_mov_b32 s11, s81
	s_lshl_b64 s[10:11], s[10:11], 2
	s_add_u32 s10, s12, s10
	s_addc_u32 s11, s13, s11
	global_load_dword v10, v3, s[10:11]
	global_load_dword v11, v[4:5], off offset:-4
	s_mov_b32 s98, s70
	s_mov_b32 s99, s81
	s_lshl_b64 s[98:99], s[98:99], 2
	s_mov_b32 s5, 0xc3000000
	s_add_u32 s98, s12, s98
	s_addc_u32 s99, s13, s99
	global_load_dword v244, v3, s[98:99]
	s_waitcnt vmcnt(0)
	v_sub_f32_e32 v10, v10, v11
	v_cmp_gt_f32_e32 vcc, s5, v10
	s_and_b64 s[20:21], vcc, exec
.LBB0_415:
	s_or_b64 exec, exec, s[18:19]
	v_cndmask_b32_e64 v10, 0, 1, s[20:21]
	v_cmp_ne_u32_e32 vcc, 0, v10
	s_and_saveexec_b64 s[10:11], s[14:15]
	s_cbranch_execz .LBB0_417
	s_mov_b32 s71, s81
	s_lshl_b64 s[14:15], s[70:71], 2
	s_add_u32 s12, s12, s14
	s_addc_u32 s13, s13, s15
	s_mov_b32 s5, 0xc3000000
	v_sub_f32_e32 v4, v244, v11
	v_cmp_gt_f32_e64 s[12:13], s5, v4
	s_and_b64 s[16:17], s[12:13], exec
